# stack: pipelined gated-merge final epilogue, ffn-in tile transition without drains, folded row-max trees in attention, norm gains loaded once per tile
# baseline (speedup 1.0000x reference)
;     __device__ __forceinline__ void operator()(const f32x4 (&acc)[2][2][4][2], const pg8::Unit& u, int wr, int wc, int fr, int fq, LAS unsigned char* sp) const {
;     ...
;             const float* gn = (pn < 2) ? qg : kg; const float osc = (pn < 2) ? C2 : ((pn == 7) ? 0.125f : 1.f);
; #pragma unroll
;             for (int ai = 0; ai < 2; ++ai)
; #pragma unroll
;                 for (int m = 0; m < 4; ++m) {
;                     const int row = row0 + ai * 128 + m * 16; const float s = rsl[ai * 128 + m * 16];
;                     f32x4 v[2][2];
; #pragma unroll
;                     for (int bj = 0; bj < 2; ++bj)
; #pragma unroll
;                         for (int n = 0; n < 2; ++n) v[bj][n] = acc[ai][bj][m][n] * s;
;                     if (act == 3) {
;                         float q = 0.f;
; #pragma unroll
;                         for (int bj = 0; bj < 2; ++bj)
; #pragma unroll
;                             for (int n = 0; n < 2; ++n) q += (v[bj][n][0] * v[bj][n][0] + v[bj][n][1] * v[bj][n][1]) + (v[bj][n][2] * v[bj][n][2] + v[bj][n][3] * v[bj][n][3]);
;                         q += __shfl_xor(q, 16); q += __shfl_xor(q, 32);
;                         const float ri = rsqrtf(q * (1.f / 64.f) + EPS) * osc;
; #pragma unroll
;                         for (int bj = 0; bj < 2; ++bj)
; #pragma unroll
;                             for (int n = 0; n < 2; ++n) { const f32x4 g = *(const f32x4*)(gn + 32 * bj + 8 * fq + 4 * n); v[bj][n] = v[bj][n] * g * ri; }
;                     } else {
;                         const int pos = row & (SEQ - 1);
; #pragma unroll
;                         for (int n = 0; n < 2; ++n) { const f32x4 cs = *(const f32x4*)(rot + pos * 32 + 8 * fq + 4 * n), sn = *(const f32x4*)(rot + 4096 * 32 + pos * 32 + 8 * fq + 4 * n);
;                             const f32x4 x1 = v[0][n], x2 = v[1][n]; v[0][n] = (x1 * cs - x2 * sn) * osc; v[1][n] = (x2 * cs + x1 * sn) * osc; }
.LBB0_348:
	s_and_b64 vcc, exec, s[66:67]
	s_cbranch_vccz .LBB0_347
	s_cmp_lt_i32 s8, 2
	s_cselect_b64 vcc, -1, 0
	s_and_b64 s[26:27], vcc, exec
	s_cselect_b32 s26, s14, s18
	s_cselect_b32 s9, s15, s19
	s_add_u32 s68, s26, s52
	s_addc_u32 s69, s9, s53
	v_mov_b32_e32 v208, v160
	v_mov_b32_e32 v209, 0
	v_lshl_add_u64 v[208:209], s[68:69], 0, v[208:209]
	global_load_dwordx4 v[212:215], v[208:209], off
	global_load_dwordx4 v[216:219], v[208:209], off offset:16
	global_load_dwordx4 v[220:223], v[208:209], off offset:144
	global_load_dwordx4 v[224:227], v[208:209], off offset:128
	ds_read_b32 v0, v203
	s_cmp_eq_u32 s8, 7
	s_cselect_b64 s[8:9], -1, 0
	v_cndmask_b32_e64 v161, 1.0, v188, s[8:9]
	s_cmp_lg_u32 s55, 3
	v_cndmask_b32_e32 v164, v161, v194, vcc
	s_cselect_b64 s[66:67], -1, 0
	v_mov_b32_e32 v165, v164
	s_waitcnt lgkmcnt(0)
	v_pk_mul_f32 v[176:177], v[128:129], v[0:1] op_sel_hi:[1,0]
	v_pk_mul_f32 v[178:179], v[126:127], v[0:1] op_sel_hi:[1,0]
	v_pk_mul_f32 v[180:181], v[124:125], v[0:1] op_sel_hi:[1,0]
	v_pk_mul_f32 v[182:183], v[122:123], v[0:1] op_sel_hi:[1,0]
	v_pk_mul_f32 v[172:173], v[120:121], v[0:1] op_sel_hi:[1,0]
	v_pk_mul_f32 v[174:175], v[118:119], v[0:1] op_sel_hi:[1,0]
	v_pk_mul_f32 v[168:169], v[116:117], v[0:1] op_sel_hi:[1,0]
	v_pk_mul_f32 v[170:171], v[114:115], v[0:1] op_sel_hi:[1,0]
	s_mov_b64 s[8:9], -1
	s_and_b64 vcc, exec, s[66:67]
	s_cbranch_vccz .LBB0_351
	v_lshlrev_b32_e32 v0, 7, v202
	v_and_b32_e32 v0, 0x7e780, v0
	v_lshl_add_u64 v[114:115], v[142:143], 0, v[0:1]
	v_lshl_add_u64 v[116:117], v[144:145], 0, v[0:1]
	global_load_dwordx4 v[122:125], v[114:115], off offset:16
	global_load_dwordx4 v[118:121], v[114:115], off
	global_load_dwordx4 v[204:207], v[116:117], off offset:16
	global_load_dwordx4 v[126:129], v[116:117], off
	v_mov_b32_e32 v192, v164
	v_mov_b32_e32 v193, v164
	s_mov_b64 s[8:9], 0
	s_waitcnt vmcnt(0)
	v_pk_mul_f32 v[114:115], v[172:173], v[128:129]
	v_pk_mul_f32 v[116:117], v[174:175], v[126:127]
	v_pk_mul_f32 v[128:129], v[176:177], v[128:129]
	v_pk_mul_f32 v[126:127], v[178:179], v[126:127]
	v_pk_fma_f32 v[114:115], v[176:177], v[120:121], v[114:115] neg_lo:[0,0,1] neg_hi:[0,0,1]
	v_pk_fma_f32 v[166:167], v[178:179], v[118:119], v[116:117] neg_lo:[0,0,1] neg_hi:[0,0,1]
	v_pk_fma_f32 v[120:121], v[172:173], v[120:121], v[128:129]
	v_pk_fma_f32 v[118:119], v[174:175], v[118:119], v[126:127]
	v_pk_mul_f32 v[128:129], v[192:193], v[120:121]
	v_pk_mul_f32 v[126:127], v[164:165], v[118:119]
	v_pk_mul_f32 v[118:119], v[168:169], v[206:207]
	v_pk_mul_f32 v[120:121], v[170:171], v[204:205]
	v_pk_mul_f32 v[116:117], v[192:193], v[114:115]
	v_pk_mul_f32 v[114:115], v[164:165], v[166:167]
	v_pk_fma_f32 v[118:119], v[180:181], v[124:125], v[118:119] neg_lo:[0,0,1] neg_hi:[0,0,1]
	v_pk_fma_f32 v[166:167], v[182:183], v[122:123], v[120:121] neg_lo:[0,0,1] neg_hi:[0,0,1]
	v_pk_mul_f32 v[120:121], v[192:193], v[118:119]
	v_pk_mul_f32 v[118:119], v[164:165], v[166:167]
	v_pk_mul_f32 v[166:167], v[180:181], v[206:207]
	v_pk_mul_f32 v[204:205], v[182:183], v[204:205]
	v_pk_fma_f32 v[124:125], v[168:169], v[124:125], v[166:167]
	v_pk_fma_f32 v[122:123], v[170:171], v[122:123], v[204:205]
	v_pk_mul_f32 v[124:125], v[192:193], v[124:125]
	v_pk_mul_f32 v[122:123], v[164:165], v[122:123]
.LBB0_351:
	v_mov_b32_e32 v161, v1
	s_andn2_b64 vcc, exec, s[8:9]
	v_lshl_add_u64 v[166:167], s[68:69], 0, v[160:161]
	s_cbranch_vccnz .LBB0_353
	v_pk_mul_f32 v[114:115], v[176:177], v[176:177]
	v_pk_mul_f32 v[116:117], v[178:179], v[178:179]
	v_mul_f32_e32 v0, v174, v174
	v_pk_mov_b32 v[118:119], v[116:117], v[114:115] op_sel:[1,0]
	v_mov_b32_e32 v117, v115
	v_pk_add_f32 v[114:115], v[118:119], v[116:117]
	v_pk_mul_f32 v[116:117], v[180:181], v[180:181]
	v_pk_mul_f32 v[118:119], v[182:183], v[182:183]
	v_pk_add_f32 v[114:115], v[114:115], v[114:115] op_sel_hi:[0,1]
	v_pk_mov_b32 v[120:121], v[118:119], v[116:117] op_sel:[1,0]
	v_mov_b32_e32 v119, v117
	v_pk_add_f32 v[116:117], v[120:121], v[118:119]
	v_pk_fma_f32 v[118:119], v[174:175], v[174:175], v[0:1] op_sel_hi:[1,1,0]
	v_mul_f32_e32 v0, v172, v172
	v_pk_add_f32 v[116:117], v[116:117], v[116:117] op_sel_hi:[0,1]
	v_pk_fma_f32 v[120:121], v[172:173], v[172:173], v[0:1] op_sel_hi:[1,1,0]
	v_mul_f32_e32 v118, v170, v170
	v_mul_f32_e32 v120, v171, v171
	v_mul_f32_e32 v114, v168, v168
	v_mul_f32_e32 v116, v169, v169
	v_pk_add_f32 v[118:119], v[118:119], v[120:121]
	v_pk_add_f32 v[114:115], v[114:115], v[116:117]
	s_nop 0
	v_pk_add_f32 v[114:115], v[118:119], v[114:115]
	s_nop 0
	v_add_f32_e32 v0, v114, v115
	v_and_b32_e32 v115, 64, v187
	v_xor_b32_e32 v114, 16, v187
	v_add_u32_e32 v115, 64, v115
	v_cmp_lt_i32_e32 vcc, v114, v115
	s_nop 1
	v_cndmask_b32_e32 v114, v187, v114, vcc
	v_lshlrev_b32_e32 v114, 2, v114
	ds_bpermute_b32 v114, v114, v0
	s_waitcnt lgkmcnt(0)
	v_add_f32_e32 v0, v0, v114
	v_xor_b32_e32 v114, 32, v187
	v_cmp_lt_i32_e32 vcc, v114, v115
	s_nop 1
	v_cndmask_b32_e32 v114, v187, v114, vcc
	v_lshlrev_b32_e32 v114, 2, v114
	ds_bpermute_b32 v114, v114, v0
	s_waitcnt lgkmcnt(0)
	v_add_f32_e32 v0, v0, v114
	v_fmamk_f32 v0, v0, 0x3c800000, v184
	v_cmp_gt_f32_e32 vcc, s74, v0
	v_mul_f32_e32 v114, 0x4b800000, v0
	s_nop 0
	v_cndmask_b32_e32 v0, v0, v114, vcc
	v_rsq_f32_e32 v0, v0
	s_nop 0
	v_mul_f32_e32 v114, 0x45800000, v0
	v_cndmask_b32_e32 v0, v0, v114, vcc
	s_waitcnt vmcnt(0)
	v_mov_b32_e32 v118, v216
	v_mov_b32_e32 v119, v217
	v_mov_b32_e32 v120, v218
	v_mov_b32_e32 v121, v219
	v_mov_b32_e32 v114, v212
	v_mov_b32_e32 v115, v213
	v_mov_b32_e32 v116, v214
	v_mov_b32_e32 v117, v215
	v_mov_b32_e32 v122, v220
	v_mov_b32_e32 v123, v221
	v_mov_b32_e32 v124, v222
	v_mov_b32_e32 v125, v223
	v_mov_b32_e32 v126, v224
	v_mov_b32_e32 v127, v225
	v_mov_b32_e32 v128, v226
	v_mov_b32_e32 v129, v227
	v_mul_f32_e32 v0, v164, v0
	v_pk_mul_f32 v[120:121], v[180:181], v[120:121]
	v_pk_mul_f32 v[116:117], v[176:177], v[116:117]
	v_pk_mul_f32 v[114:115], v[178:179], v[114:115]
	v_pk_mul_f32 v[118:119], v[182:183], v[118:119]
	v_pk_mul_f32 v[128:129], v[172:173], v[128:129]
	v_pk_mul_f32 v[126:127], v[174:175], v[126:127]
	v_pk_mul_f32 v[124:125], v[168:169], v[124:125]
	v_pk_mul_f32 v[122:123], v[170:171], v[122:123]
	v_pk_mul_f32 v[116:117], v[116:117], v[0:1] op_sel_hi:[1,0]
	v_pk_mul_f32 v[114:115], v[114:115], v[0:1] op_sel_hi:[1,0]
	v_pk_mul_f32 v[120:121], v[120:121], v[0:1] op_sel_hi:[1,0]
	v_pk_mul_f32 v[118:119], v[118:119], v[0:1] op_sel_hi:[1,0]
	v_pk_mul_f32 v[128:129], v[128:129], v[0:1] op_sel_hi:[1,0]
	v_pk_mul_f32 v[126:127], v[126:127], v[0:1] op_sel_hi:[1,0]
	v_pk_mul_f32 v[124:125], v[124:125], v[0:1] op_sel_hi:[1,0]
	v_pk_mul_f32 v[122:123], v[122:123], v[0:1] op_sel_hi:[1,0]

;     __device__ __forceinline__ void operator()(const f32x4 (&acc)[2][2][4][2], const pg8::Unit& u, int wr, int wc, int fr, int fq, LAS unsigned char* sp) const {
;     ...
;                     if (act == 3) {
;                         float q = 0.f;
; #pragma unroll
;                         for (int bj = 0; bj < 2; ++bj)
; #pragma unroll
;                             for (int n = 0; n < 2; ++n) q += (v[bj][n][0] * v[bj][n][0] + v[bj][n][1] * v[bj][n][1]) + (v[bj][n][2] * v[bj][n][2] + v[bj][n][3] * v[bj][n][3]);
;                         q += __shfl_xor(q, 16); q += __shfl_xor(q, 32);
;                         const float ri = rsqrtf(q * (1.f / 64.f) + EPS) * osc;
; #pragma unroll
;                         for (int bj = 0; bj < 2; ++bj)
; #pragma unroll
;                             for (int n = 0; n < 2; ++n) { const f32x4 g = *(const f32x4*)(gn + 32 * bj + 8 * fq + 4 * n); v[bj][n] = v[bj][n] * g * ri; }
.LBB0_355:
	s_andn2_b64 vcc, exec, s[64:65]
	s_cbranch_vccnz .LBB0_357
	v_pk_mul_f32 v[98:99], v[122:123], v[122:123]
	v_pk_mul_f32 v[100:101], v[124:125], v[124:125]
	v_mul_f32_e32 v0, v120, v120
	v_pk_mov_b32 v[102:103], v[100:101], v[98:99] op_sel:[1,0]
	v_mov_b32_e32 v101, v99
	v_pk_add_f32 v[98:99], v[102:103], v[100:101]
	v_pk_mul_f32 v[100:101], v[126:127], v[126:127]
	v_pk_mul_f32 v[102:103], v[128:129], v[128:129]
	v_pk_add_f32 v[98:99], v[98:99], v[98:99] op_sel_hi:[0,1]
	v_pk_mov_b32 v[104:105], v[102:103], v[100:101] op_sel:[1,0]
	v_mov_b32_e32 v103, v101
	v_pk_add_f32 v[100:101], v[104:105], v[102:103]
	v_pk_fma_f32 v[102:103], v[120:121], v[120:121], v[0:1] op_sel_hi:[1,1,0]
	v_mul_f32_e32 v0, v118, v118
	v_pk_add_f32 v[100:101], v[100:101], v[100:101] op_sel_hi:[0,1]
	v_pk_fma_f32 v[104:105], v[118:119], v[118:119], v[0:1] op_sel_hi:[1,1,0]
	v_mul_f32_e32 v102, v116, v116
	v_mul_f32_e32 v104, v117, v117
	v_mul_f32_e32 v98, v114, v114
	v_mul_f32_e32 v100, v115, v115
	v_pk_add_f32 v[102:103], v[102:103], v[104:105]
	v_pk_add_f32 v[98:99], v[98:99], v[100:101]
	s_nop 0
	v_pk_add_f32 v[98:99], v[102:103], v[98:99]
	s_nop 0
	v_add_f32_e32 v0, v98, v99
	v_and_b32_e32 v99, 64, v187
	v_xor_b32_e32 v98, 16, v187
	v_add_u32_e32 v99, 64, v99
	v_cmp_lt_i32_e32 vcc, v98, v99
	s_nop 1
	v_cndmask_b32_e32 v98, v187, v98, vcc
	v_lshlrev_b32_e32 v98, 2, v98
	ds_bpermute_b32 v98, v98, v0
	s_waitcnt lgkmcnt(0)
	v_add_f32_e32 v0, v0, v98
	v_xor_b32_e32 v98, 32, v187
	v_cmp_lt_i32_e32 vcc, v98, v99
	s_nop 1
	v_cndmask_b32_e32 v98, v187, v98, vcc
	v_lshlrev_b32_e32 v98, 2, v98
	ds_bpermute_b32 v98, v98, v0
	s_waitcnt lgkmcnt(0)
	v_add_f32_e32 v0, v0, v98
	v_fmamk_f32 v0, v0, 0x3c800000, v184
	v_cmp_gt_f32_e32 vcc, s74, v0
	v_mul_f32_e32 v98, 0x4b800000, v0
	s_nop 0
	v_cndmask_b32_e32 v0, v0, v98, vcc
	v_rsq_f32_e32 v0, v0
	s_nop 0
	v_mul_f32_e32 v98, 0x45800000, v0
	v_cndmask_b32_e32 v0, v0, v98, vcc
	v_mov_b32_e32 v102, v216
	v_mov_b32_e32 v103, v217
	v_mov_b32_e32 v104, v218
	v_mov_b32_e32 v105, v219
	v_mov_b32_e32 v98, v212
	v_mov_b32_e32 v99, v213
	v_mov_b32_e32 v100, v214
	v_mov_b32_e32 v101, v215
	v_mov_b32_e32 v106, v220
	v_mov_b32_e32 v107, v221
	v_mov_b32_e32 v108, v222
	v_mov_b32_e32 v109, v223
	v_mov_b32_e32 v110, v224
	v_mov_b32_e32 v111, v225
	v_mov_b32_e32 v112, v226
	v_mov_b32_e32 v113, v227
	v_mul_f32_e32 v0, v164, v0
	v_pk_mul_f32 v[104:105], v[126:127], v[104:105]
	v_pk_mul_f32 v[100:101], v[122:123], v[100:101]
	v_pk_mul_f32 v[98:99], v[124:125], v[98:99]
	v_pk_mul_f32 v[102:103], v[128:129], v[102:103]
	v_pk_mul_f32 v[112:113], v[118:119], v[112:113]
	v_pk_mul_f32 v[110:111], v[120:121], v[110:111]
	v_pk_mul_f32 v[108:109], v[114:115], v[108:109]
	v_pk_mul_f32 v[106:107], v[116:117], v[106:107]
	v_pk_mul_f32 v[100:101], v[100:101], v[0:1] op_sel_hi:[1,0]
	v_pk_mul_f32 v[98:99], v[98:99], v[0:1] op_sel_hi:[1,0]
	v_pk_mul_f32 v[104:105], v[104:105], v[0:1] op_sel_hi:[1,0]
	v_pk_mul_f32 v[102:103], v[102:103], v[0:1] op_sel_hi:[1,0]
	v_pk_mul_f32 v[112:113], v[112:113], v[0:1] op_sel_hi:[1,0]
	v_pk_mul_f32 v[110:111], v[110:111], v[0:1] op_sel_hi:[1,0]
	v_pk_mul_f32 v[108:109], v[108:109], v[0:1] op_sel_hi:[1,0]
	v_pk_mul_f32 v[106:107], v[106:107], v[0:1] op_sel_hi:[1,0]

;     __device__ __forceinline__ void operator()(const f32x4 (&acc)[2][2][4][2], const pg8::Unit& u, int wr, int wc, int fr, int fq, LAS unsigned char* sp) const {
;     ...
;                     if (act == 3) {
;                         float q = 0.f;
; #pragma unroll
;                         for (int bj = 0; bj < 2; ++bj)
; #pragma unroll
;                             for (int n = 0; n < 2; ++n) q += (v[bj][n][0] * v[bj][n][0] + v[bj][n][1] * v[bj][n][1]) + (v[bj][n][2] * v[bj][n][2] + v[bj][n][3] * v[bj][n][3]);
;                         q += __shfl_xor(q, 16); q += __shfl_xor(q, 32);
;                         const float ri = rsqrtf(q * (1.f / 64.f) + EPS) * osc;
; #pragma unroll
;                         for (int bj = 0; bj < 2; ++bj)
; #pragma unroll
;                             for (int n = 0; n < 2; ++n) { const f32x4 g = *(const f32x4*)(gn + 32 * bj + 8 * fq + 4 * n); v[bj][n] = v[bj][n] * g * ri; }
.LBB0_359:
	s_andn2_b64 vcc, exec, s[64:65]
	s_cbranch_vccnz .LBB0_361
	v_pk_mul_f32 v[82:83], v[106:107], v[106:107]
	v_pk_mul_f32 v[84:85], v[108:109], v[108:109]
	v_mul_f32_e32 v0, v104, v104
	v_pk_mov_b32 v[86:87], v[84:85], v[82:83] op_sel:[1,0]
	v_mov_b32_e32 v85, v83
	v_pk_add_f32 v[82:83], v[86:87], v[84:85]
	v_pk_mul_f32 v[84:85], v[110:111], v[110:111]
	v_pk_mul_f32 v[86:87], v[112:113], v[112:113]
	v_pk_add_f32 v[82:83], v[82:83], v[82:83] op_sel_hi:[0,1]
	v_pk_mov_b32 v[88:89], v[86:87], v[84:85] op_sel:[1,0]
	v_mov_b32_e32 v87, v85
	v_pk_add_f32 v[84:85], v[88:89], v[86:87]
	v_pk_fma_f32 v[86:87], v[104:105], v[104:105], v[0:1] op_sel_hi:[1,1,0]
	v_mul_f32_e32 v0, v102, v102
	v_pk_add_f32 v[84:85], v[84:85], v[84:85] op_sel_hi:[0,1]
	v_pk_fma_f32 v[88:89], v[102:103], v[102:103], v[0:1] op_sel_hi:[1,1,0]
	v_mul_f32_e32 v86, v100, v100
	v_mul_f32_e32 v88, v101, v101
	v_mul_f32_e32 v82, v98, v98
	v_mul_f32_e32 v84, v99, v99
	v_pk_add_f32 v[86:87], v[86:87], v[88:89]
	v_pk_add_f32 v[82:83], v[82:83], v[84:85]
	s_nop 0
	v_pk_add_f32 v[82:83], v[86:87], v[82:83]
	s_nop 0
	v_add_f32_e32 v0, v82, v83
	v_and_b32_e32 v83, 64, v187
	v_xor_b32_e32 v82, 16, v187
	v_add_u32_e32 v83, 64, v83
	v_cmp_lt_i32_e32 vcc, v82, v83
	s_nop 1
	v_cndmask_b32_e32 v82, v187, v82, vcc
	v_lshlrev_b32_e32 v82, 2, v82
	ds_bpermute_b32 v82, v82, v0
	s_waitcnt lgkmcnt(0)
	v_add_f32_e32 v0, v0, v82
	v_xor_b32_e32 v82, 32, v187
	v_cmp_lt_i32_e32 vcc, v82, v83
	s_nop 1
	v_cndmask_b32_e32 v82, v187, v82, vcc
	v_lshlrev_b32_e32 v82, 2, v82
	ds_bpermute_b32 v82, v82, v0
	s_waitcnt lgkmcnt(0)
	v_add_f32_e32 v0, v0, v82
	v_fmamk_f32 v0, v0, 0x3c800000, v184
	v_cmp_gt_f32_e32 vcc, s74, v0
	v_mul_f32_e32 v82, 0x4b800000, v0
	s_nop 0
	v_cndmask_b32_e32 v0, v0, v82, vcc
	v_rsq_f32_e32 v0, v0
	s_nop 0
	v_mul_f32_e32 v82, 0x45800000, v0
	v_cndmask_b32_e32 v0, v0, v82, vcc
	v_mov_b32_e32 v86, v216
	v_mov_b32_e32 v87, v217
	v_mov_b32_e32 v88, v218
	v_mov_b32_e32 v89, v219
	v_mov_b32_e32 v82, v212
	v_mov_b32_e32 v83, v213
	v_mov_b32_e32 v84, v214
	v_mov_b32_e32 v85, v215
	v_mov_b32_e32 v90, v220
	v_mov_b32_e32 v91, v221
	v_mov_b32_e32 v92, v222
	v_mov_b32_e32 v93, v223
	v_mov_b32_e32 v94, v224
	v_mov_b32_e32 v95, v225
	v_mov_b32_e32 v96, v226
	v_mov_b32_e32 v97, v227
	v_mul_f32_e32 v0, v164, v0
	v_pk_mul_f32 v[88:89], v[110:111], v[88:89]
	v_pk_mul_f32 v[84:85], v[106:107], v[84:85]
	v_pk_mul_f32 v[82:83], v[108:109], v[82:83]
	v_pk_mul_f32 v[86:87], v[112:113], v[86:87]
	v_pk_mul_f32 v[96:97], v[102:103], v[96:97]
	v_pk_mul_f32 v[94:95], v[104:105], v[94:95]
	v_pk_mul_f32 v[92:93], v[98:99], v[92:93]
	v_pk_mul_f32 v[90:91], v[100:101], v[90:91]
	v_pk_mul_f32 v[84:85], v[84:85], v[0:1] op_sel_hi:[1,0]
	v_pk_mul_f32 v[82:83], v[82:83], v[0:1] op_sel_hi:[1,0]
	v_pk_mul_f32 v[88:89], v[88:89], v[0:1] op_sel_hi:[1,0]
	v_pk_mul_f32 v[86:87], v[86:87], v[0:1] op_sel_hi:[1,0]
	v_pk_mul_f32 v[96:97], v[96:97], v[0:1] op_sel_hi:[1,0]
	v_pk_mul_f32 v[94:95], v[94:95], v[0:1] op_sel_hi:[1,0]
	v_pk_mul_f32 v[92:93], v[92:93], v[0:1] op_sel_hi:[1,0]
	v_pk_mul_f32 v[90:91], v[90:91], v[0:1] op_sel_hi:[1,0]

;     __device__ __forceinline__ void operator()(const f32x4 (&acc)[2][2][4][2], const pg8::Unit& u, int wr, int wc, int fr, int fq, LAS unsigned char* sp) const {
;     ...
;                     if (act == 3) {
;                         float q = 0.f;
; #pragma unroll
;                         for (int bj = 0; bj < 2; ++bj)
; #pragma unroll
;                             for (int n = 0; n < 2; ++n) q += (v[bj][n][0] * v[bj][n][0] + v[bj][n][1] * v[bj][n][1]) + (v[bj][n][2] * v[bj][n][2] + v[bj][n][3] * v[bj][n][3]);
;                         q += __shfl_xor(q, 16); q += __shfl_xor(q, 32);
;                         const float ri = rsqrtf(q * (1.f / 64.f) + EPS) * osc;
; #pragma unroll
;                         for (int bj = 0; bj < 2; ++bj)
; #pragma unroll
;                             for (int n = 0; n < 2; ++n) { const f32x4 g = *(const f32x4*)(gn + 32 * bj + 8 * fq + 4 * n); v[bj][n] = v[bj][n] * g * ri; }
.LBB0_363:
	s_andn2_b64 vcc, exec, s[64:65]
	s_cbranch_vccnz .LBB0_365
	v_pk_mul_f32 v[66:67], v[90:91], v[90:91]
	v_pk_mul_f32 v[68:69], v[92:93], v[92:93]
	v_mul_f32_e32 v0, v88, v88
	v_pk_mov_b32 v[70:71], v[68:69], v[66:67] op_sel:[1,0]
	v_mov_b32_e32 v69, v67
	v_pk_add_f32 v[66:67], v[70:71], v[68:69]
	v_pk_mul_f32 v[68:69], v[94:95], v[94:95]
	v_pk_mul_f32 v[70:71], v[96:97], v[96:97]
	v_pk_add_f32 v[66:67], v[66:67], v[66:67] op_sel_hi:[0,1]
	v_pk_mov_b32 v[72:73], v[70:71], v[68:69] op_sel:[1,0]
	v_mov_b32_e32 v71, v69
	v_pk_add_f32 v[68:69], v[72:73], v[70:71]
	v_pk_fma_f32 v[70:71], v[88:89], v[88:89], v[0:1] op_sel_hi:[1,1,0]
	v_mul_f32_e32 v0, v86, v86
	v_pk_add_f32 v[68:69], v[68:69], v[68:69] op_sel_hi:[0,1]
	v_pk_fma_f32 v[72:73], v[86:87], v[86:87], v[0:1] op_sel_hi:[1,1,0]
	v_mul_f32_e32 v70, v84, v84
	v_mul_f32_e32 v72, v85, v85
	v_mul_f32_e32 v66, v82, v82
	v_mul_f32_e32 v68, v83, v83
	v_pk_add_f32 v[70:71], v[70:71], v[72:73]
	v_pk_add_f32 v[66:67], v[66:67], v[68:69]
	s_nop 0
	v_pk_add_f32 v[66:67], v[70:71], v[66:67]
	s_nop 0
	v_add_f32_e32 v0, v66, v67
	v_and_b32_e32 v67, 64, v187
	v_xor_b32_e32 v66, 16, v187
	v_add_u32_e32 v67, 64, v67
	v_cmp_lt_i32_e32 vcc, v66, v67
	s_nop 1
	v_cndmask_b32_e32 v66, v187, v66, vcc
	v_lshlrev_b32_e32 v66, 2, v66
	ds_bpermute_b32 v66, v66, v0
	s_waitcnt lgkmcnt(0)
	v_add_f32_e32 v0, v0, v66
	v_xor_b32_e32 v66, 32, v187
	v_cmp_lt_i32_e32 vcc, v66, v67
	s_nop 1
	v_cndmask_b32_e32 v66, v187, v66, vcc
	v_lshlrev_b32_e32 v66, 2, v66
	ds_bpermute_b32 v66, v66, v0
	s_waitcnt lgkmcnt(0)
	v_add_f32_e32 v0, v0, v66
	v_fmamk_f32 v0, v0, 0x3c800000, v184
	v_cmp_gt_f32_e32 vcc, s74, v0
	v_mul_f32_e32 v66, 0x4b800000, v0
	s_nop 0
	v_cndmask_b32_e32 v0, v0, v66, vcc
	v_rsq_f32_e32 v0, v0
	s_nop 0
	v_mul_f32_e32 v66, 0x45800000, v0
	v_cndmask_b32_e32 v0, v0, v66, vcc
	v_mov_b32_e32 v70, v216
	v_mov_b32_e32 v71, v217
	v_mov_b32_e32 v72, v218
	v_mov_b32_e32 v73, v219
	v_mov_b32_e32 v66, v212
	v_mov_b32_e32 v67, v213
	v_mov_b32_e32 v68, v214
	v_mov_b32_e32 v69, v215
	v_mov_b32_e32 v74, v220
	v_mov_b32_e32 v75, v221
	v_mov_b32_e32 v76, v222
	v_mov_b32_e32 v77, v223
	v_mov_b32_e32 v78, v224
	v_mov_b32_e32 v79, v225
	v_mov_b32_e32 v80, v226
	v_mov_b32_e32 v81, v227
	v_mul_f32_e32 v0, v164, v0
	v_pk_mul_f32 v[72:73], v[94:95], v[72:73]
	v_pk_mul_f32 v[68:69], v[90:91], v[68:69]
	v_pk_mul_f32 v[66:67], v[92:93], v[66:67]
	v_pk_mul_f32 v[70:71], v[96:97], v[70:71]
	v_pk_mul_f32 v[80:81], v[86:87], v[80:81]
	v_pk_mul_f32 v[78:79], v[88:89], v[78:79]
	v_pk_mul_f32 v[76:77], v[82:83], v[76:77]
	v_pk_mul_f32 v[74:75], v[84:85], v[74:75]
	v_pk_mul_f32 v[68:69], v[68:69], v[0:1] op_sel_hi:[1,0]
	v_pk_mul_f32 v[66:67], v[66:67], v[0:1] op_sel_hi:[1,0]
	v_pk_mul_f32 v[72:73], v[72:73], v[0:1] op_sel_hi:[1,0]
	v_pk_mul_f32 v[70:71], v[70:71], v[0:1] op_sel_hi:[1,0]
	v_pk_mul_f32 v[80:81], v[80:81], v[0:1] op_sel_hi:[1,0]
	v_pk_mul_f32 v[78:79], v[78:79], v[0:1] op_sel_hi:[1,0]
	v_pk_mul_f32 v[76:77], v[76:77], v[0:1] op_sel_hi:[1,0]
	v_pk_mul_f32 v[74:75], v[74:75], v[0:1] op_sel_hi:[1,0]

;     __device__ __forceinline__ void operator()(const f32x4 (&acc)[2][2][4][2], const pg8::Unit& u, int wr, int wc, int fr, int fq, LAS unsigned char* sp) const {
;     ...
;                     if (act == 3) {
;                         float q = 0.f;
; #pragma unroll
;                         for (int bj = 0; bj < 2; ++bj)
; #pragma unroll
;                             for (int n = 0; n < 2; ++n) q += (v[bj][n][0] * v[bj][n][0] + v[bj][n][1] * v[bj][n][1]) + (v[bj][n][2] * v[bj][n][2] + v[bj][n][3] * v[bj][n][3]);
;                         q += __shfl_xor(q, 16); q += __shfl_xor(q, 32);
;                         const float ri = rsqrtf(q * (1.f / 64.f) + EPS) * osc;
; #pragma unroll
;                         for (int bj = 0; bj < 2; ++bj)
; #pragma unroll
;                             for (int n = 0; n < 2; ++n) { const f32x4 g = *(const f32x4*)(gn + 32 * bj + 8 * fq + 4 * n); v[bj][n] = v[bj][n] * g * ri; }
.LBB0_367:
	s_andn2_b64 vcc, exec, s[64:65]
	s_cbranch_vccnz .LBB0_369
	v_pk_mul_f32 v[50:51], v[74:75], v[74:75]
	v_pk_mul_f32 v[52:53], v[76:77], v[76:77]
	v_mul_f32_e32 v0, v72, v72
	v_pk_mov_b32 v[54:55], v[52:53], v[50:51] op_sel:[1,0]
	v_mov_b32_e32 v53, v51
	v_pk_add_f32 v[50:51], v[54:55], v[52:53]
	v_pk_mul_f32 v[52:53], v[78:79], v[78:79]
	v_pk_mul_f32 v[54:55], v[80:81], v[80:81]
	v_pk_add_f32 v[50:51], v[50:51], v[50:51] op_sel_hi:[0,1]
	v_pk_mov_b32 v[56:57], v[54:55], v[52:53] op_sel:[1,0]
	v_mov_b32_e32 v55, v53
	v_pk_add_f32 v[52:53], v[56:57], v[54:55]
	v_pk_fma_f32 v[54:55], v[72:73], v[72:73], v[0:1] op_sel_hi:[1,1,0]
	v_mul_f32_e32 v0, v70, v70
	v_pk_add_f32 v[52:53], v[52:53], v[52:53] op_sel_hi:[0,1]
	v_pk_fma_f32 v[56:57], v[70:71], v[70:71], v[0:1] op_sel_hi:[1,1,0]
	v_mul_f32_e32 v54, v68, v68
	v_mul_f32_e32 v56, v69, v69
	v_mul_f32_e32 v50, v66, v66
	v_mul_f32_e32 v52, v67, v67
	v_pk_add_f32 v[54:55], v[54:55], v[56:57]
	v_pk_add_f32 v[50:51], v[50:51], v[52:53]
	s_nop 0
	v_pk_add_f32 v[50:51], v[54:55], v[50:51]
	s_nop 0
	v_add_f32_e32 v0, v50, v51
	v_and_b32_e32 v51, 64, v187
	v_xor_b32_e32 v50, 16, v187
	v_add_u32_e32 v51, 64, v51
	v_cmp_lt_i32_e32 vcc, v50, v51
	s_nop 1
	v_cndmask_b32_e32 v50, v187, v50, vcc
	v_lshlrev_b32_e32 v50, 2, v50
	ds_bpermute_b32 v50, v50, v0
	s_waitcnt lgkmcnt(0)
	v_add_f32_e32 v0, v0, v50
	v_xor_b32_e32 v50, 32, v187
	v_cmp_lt_i32_e32 vcc, v50, v51
	s_nop 1
	v_cndmask_b32_e32 v50, v187, v50, vcc
	v_lshlrev_b32_e32 v50, 2, v50
	ds_bpermute_b32 v50, v50, v0
	s_waitcnt lgkmcnt(0)
	v_add_f32_e32 v0, v0, v50
	v_fmamk_f32 v0, v0, 0x3c800000, v184
	v_cmp_gt_f32_e32 vcc, s74, v0
	v_mul_f32_e32 v50, 0x4b800000, v0
	s_nop 0
	v_cndmask_b32_e32 v0, v0, v50, vcc
	v_rsq_f32_e32 v0, v0
	s_nop 0
	v_mul_f32_e32 v50, 0x45800000, v0
	v_cndmask_b32_e32 v0, v0, v50, vcc
	v_mov_b32_e32 v54, v216
	v_mov_b32_e32 v55, v217
	v_mov_b32_e32 v56, v218
	v_mov_b32_e32 v57, v219
	v_mov_b32_e32 v50, v212
	v_mov_b32_e32 v51, v213
	v_mov_b32_e32 v52, v214
	v_mov_b32_e32 v53, v215
	v_mov_b32_e32 v58, v220
	v_mov_b32_e32 v59, v221
	v_mov_b32_e32 v60, v222
	v_mov_b32_e32 v61, v223
	v_mov_b32_e32 v62, v224
	v_mov_b32_e32 v63, v225
	v_mov_b32_e32 v64, v226
	v_mov_b32_e32 v65, v227
	v_mul_f32_e32 v0, v164, v0
	v_pk_mul_f32 v[56:57], v[78:79], v[56:57]
	v_pk_mul_f32 v[52:53], v[74:75], v[52:53]
	v_pk_mul_f32 v[50:51], v[76:77], v[50:51]
	v_pk_mul_f32 v[54:55], v[80:81], v[54:55]
	v_pk_mul_f32 v[64:65], v[70:71], v[64:65]
	v_pk_mul_f32 v[62:63], v[72:73], v[62:63]
	v_pk_mul_f32 v[60:61], v[66:67], v[60:61]
	v_pk_mul_f32 v[58:59], v[68:69], v[58:59]
	v_pk_mul_f32 v[52:53], v[52:53], v[0:1] op_sel_hi:[1,0]
	v_pk_mul_f32 v[50:51], v[50:51], v[0:1] op_sel_hi:[1,0]
	v_pk_mul_f32 v[56:57], v[56:57], v[0:1] op_sel_hi:[1,0]
	v_pk_mul_f32 v[54:55], v[54:55], v[0:1] op_sel_hi:[1,0]
	v_pk_mul_f32 v[64:65], v[64:65], v[0:1] op_sel_hi:[1,0]
	v_pk_mul_f32 v[62:63], v[62:63], v[0:1] op_sel_hi:[1,0]
	v_pk_mul_f32 v[60:61], v[60:61], v[0:1] op_sel_hi:[1,0]
	v_pk_mul_f32 v[58:59], v[58:59], v[0:1] op_sel_hi:[1,0]

;     __device__ __forceinline__ void operator()(const f32x4 (&acc)[2][2][4][2], const pg8::Unit& u, int wr, int wc, int fr, int fq, LAS unsigned char* sp) const {
;     ...
;                     if (act == 3) {
;                         float q = 0.f;
; #pragma unroll
;                         for (int bj = 0; bj < 2; ++bj)
; #pragma unroll
;                             for (int n = 0; n < 2; ++n) q += (v[bj][n][0] * v[bj][n][0] + v[bj][n][1] * v[bj][n][1]) + (v[bj][n][2] * v[bj][n][2] + v[bj][n][3] * v[bj][n][3]);
;                         q += __shfl_xor(q, 16); q += __shfl_xor(q, 32);
;                         const float ri = rsqrtf(q * (1.f / 64.f) + EPS) * osc;
; #pragma unroll
;                         for (int bj = 0; bj < 2; ++bj)
; #pragma unroll
;                             for (int n = 0; n < 2; ++n) { const f32x4 g = *(const f32x4*)(gn + 32 * bj + 8 * fq + 4 * n); v[bj][n] = v[bj][n] * g * ri; }
.LBB0_371:
	s_andn2_b64 vcc, exec, s[64:65]
	s_cbranch_vccnz .LBB0_373
	v_pk_mul_f32 v[34:35], v[58:59], v[58:59]
	v_pk_mul_f32 v[36:37], v[60:61], v[60:61]
	v_mul_f32_e32 v0, v56, v56
	v_pk_mov_b32 v[38:39], v[36:37], v[34:35] op_sel:[1,0]
	v_mov_b32_e32 v37, v35
	v_pk_add_f32 v[34:35], v[38:39], v[36:37]
	v_pk_mul_f32 v[36:37], v[62:63], v[62:63]
	v_pk_mul_f32 v[38:39], v[64:65], v[64:65]
	v_pk_add_f32 v[34:35], v[34:35], v[34:35] op_sel_hi:[0,1]
	v_pk_mov_b32 v[40:41], v[38:39], v[36:37] op_sel:[1,0]
	v_mov_b32_e32 v39, v37
	v_pk_add_f32 v[36:37], v[40:41], v[38:39]
	v_pk_fma_f32 v[38:39], v[56:57], v[56:57], v[0:1] op_sel_hi:[1,1,0]
	v_mul_f32_e32 v0, v54, v54
	v_pk_add_f32 v[36:37], v[36:37], v[36:37] op_sel_hi:[0,1]
	v_pk_fma_f32 v[40:41], v[54:55], v[54:55], v[0:1] op_sel_hi:[1,1,0]
	v_mul_f32_e32 v38, v52, v52
	v_mul_f32_e32 v40, v53, v53
	v_mul_f32_e32 v34, v50, v50
	v_mul_f32_e32 v36, v51, v51
	v_pk_add_f32 v[38:39], v[38:39], v[40:41]
	v_pk_add_f32 v[34:35], v[34:35], v[36:37]
	s_nop 0
	v_pk_add_f32 v[34:35], v[38:39], v[34:35]
	s_nop 0
	v_add_f32_e32 v0, v34, v35
	v_and_b32_e32 v35, 64, v187
	v_xor_b32_e32 v34, 16, v187
	v_add_u32_e32 v35, 64, v35
	v_cmp_lt_i32_e32 vcc, v34, v35
	s_nop 1
	v_cndmask_b32_e32 v34, v187, v34, vcc
	v_lshlrev_b32_e32 v34, 2, v34
	ds_bpermute_b32 v34, v34, v0
	s_waitcnt lgkmcnt(0)
	v_add_f32_e32 v0, v0, v34
	v_xor_b32_e32 v34, 32, v187
	v_cmp_lt_i32_e32 vcc, v34, v35
	s_nop 1
	v_cndmask_b32_e32 v34, v187, v34, vcc
	v_lshlrev_b32_e32 v34, 2, v34
	ds_bpermute_b32 v34, v34, v0
	s_waitcnt lgkmcnt(0)
	v_add_f32_e32 v0, v0, v34
	v_fmamk_f32 v0, v0, 0x3c800000, v184
	v_cmp_gt_f32_e32 vcc, s74, v0
	v_mul_f32_e32 v34, 0x4b800000, v0
	s_nop 0
	v_cndmask_b32_e32 v0, v0, v34, vcc
	v_rsq_f32_e32 v0, v0
	s_nop 0
	v_mul_f32_e32 v34, 0x45800000, v0
	v_cndmask_b32_e32 v0, v0, v34, vcc
	v_mov_b32_e32 v38, v216
	v_mov_b32_e32 v39, v217
	v_mov_b32_e32 v40, v218
	v_mov_b32_e32 v41, v219
	v_mov_b32_e32 v34, v212
	v_mov_b32_e32 v35, v213
	v_mov_b32_e32 v36, v214
	v_mov_b32_e32 v37, v215
	v_mov_b32_e32 v42, v220
	v_mov_b32_e32 v43, v221
	v_mov_b32_e32 v44, v222
	v_mov_b32_e32 v45, v223
	v_mov_b32_e32 v46, v224
	v_mov_b32_e32 v47, v225
	v_mov_b32_e32 v48, v226
	v_mov_b32_e32 v49, v227
	v_mul_f32_e32 v0, v164, v0
	v_pk_mul_f32 v[40:41], v[62:63], v[40:41]
	v_pk_mul_f32 v[36:37], v[58:59], v[36:37]
	v_pk_mul_f32 v[34:35], v[60:61], v[34:35]
	v_pk_mul_f32 v[38:39], v[64:65], v[38:39]
	v_pk_mul_f32 v[48:49], v[54:55], v[48:49]
	v_pk_mul_f32 v[46:47], v[56:57], v[46:47]
	v_pk_mul_f32 v[44:45], v[50:51], v[44:45]
	v_pk_mul_f32 v[42:43], v[52:53], v[42:43]
	v_pk_mul_f32 v[36:37], v[36:37], v[0:1] op_sel_hi:[1,0]
	v_pk_mul_f32 v[34:35], v[34:35], v[0:1] op_sel_hi:[1,0]
	v_pk_mul_f32 v[40:41], v[40:41], v[0:1] op_sel_hi:[1,0]
	v_pk_mul_f32 v[38:39], v[38:39], v[0:1] op_sel_hi:[1,0]
	v_pk_mul_f32 v[48:49], v[48:49], v[0:1] op_sel_hi:[1,0]
	v_pk_mul_f32 v[46:47], v[46:47], v[0:1] op_sel_hi:[1,0]
	v_pk_mul_f32 v[44:45], v[44:45], v[0:1] op_sel_hi:[1,0]
	v_pk_mul_f32 v[42:43], v[42:43], v[0:1] op_sel_hi:[1,0]

;     __device__ __forceinline__ void operator()(const f32x4 (&acc)[2][2][4][2], const pg8::Unit& u, int wr, int wc, int fr, int fq, LAS unsigned char* sp) const {
;     ...
;                     if (act == 3) {
;                         float q = 0.f;
; #pragma unroll
;                         for (int bj = 0; bj < 2; ++bj)
; #pragma unroll
;                             for (int n = 0; n < 2; ++n) q += (v[bj][n][0] * v[bj][n][0] + v[bj][n][1] * v[bj][n][1]) + (v[bj][n][2] * v[bj][n][2] + v[bj][n][3] * v[bj][n][3]);
;                         q += __shfl_xor(q, 16); q += __shfl_xor(q, 32);
;                         const float ri = rsqrtf(q * (1.f / 64.f) + EPS) * osc;
; #pragma unroll
;                         for (int bj = 0; bj < 2; ++bj)
; #pragma unroll
;                             for (int n = 0; n < 2; ++n) { const f32x4 g = *(const f32x4*)(gn + 32 * bj + 8 * fq + 4 * n); v[bj][n] = v[bj][n] * g * ri; }
.LBB0_375:
	s_andn2_b64 vcc, exec, s[64:65]
	s_cbranch_vccnz .LBB0_377
	v_pk_mul_f32 v[18:19], v[42:43], v[42:43]
	v_pk_mul_f32 v[20:21], v[44:45], v[44:45]
	v_mul_f32_e32 v0, v40, v40
	v_pk_mov_b32 v[22:23], v[20:21], v[18:19] op_sel:[1,0]
	v_mov_b32_e32 v21, v19
	v_pk_add_f32 v[18:19], v[22:23], v[20:21]
	v_pk_mul_f32 v[20:21], v[46:47], v[46:47]
	v_pk_mul_f32 v[22:23], v[48:49], v[48:49]
	v_pk_add_f32 v[18:19], v[18:19], v[18:19] op_sel_hi:[0,1]
	v_pk_mov_b32 v[24:25], v[22:23], v[20:21] op_sel:[1,0]
	v_mov_b32_e32 v23, v21
	v_pk_add_f32 v[20:21], v[24:25], v[22:23]
	v_pk_fma_f32 v[22:23], v[40:41], v[40:41], v[0:1] op_sel_hi:[1,1,0]
	v_mul_f32_e32 v0, v38, v38
	v_pk_add_f32 v[20:21], v[20:21], v[20:21] op_sel_hi:[0,1]
	v_pk_fma_f32 v[24:25], v[38:39], v[38:39], v[0:1] op_sel_hi:[1,1,0]
	v_mul_f32_e32 v22, v36, v36
	v_mul_f32_e32 v24, v37, v37
	v_mul_f32_e32 v18, v34, v34
	v_mul_f32_e32 v20, v35, v35
	v_pk_add_f32 v[22:23], v[22:23], v[24:25]
	v_pk_add_f32 v[18:19], v[18:19], v[20:21]
	s_nop 0
	v_pk_add_f32 v[18:19], v[22:23], v[18:19]
	s_nop 0
	v_add_f32_e32 v0, v18, v19
	v_and_b32_e32 v19, 64, v187
	v_xor_b32_e32 v18, 16, v187
	v_add_u32_e32 v19, 64, v19
	v_cmp_lt_i32_e32 vcc, v18, v19
	s_nop 1
	v_cndmask_b32_e32 v18, v187, v18, vcc
	v_lshlrev_b32_e32 v18, 2, v18
	ds_bpermute_b32 v18, v18, v0
	s_waitcnt lgkmcnt(0)
	v_add_f32_e32 v0, v0, v18
	v_xor_b32_e32 v18, 32, v187
	v_cmp_lt_i32_e32 vcc, v18, v19
	s_nop 1
	v_cndmask_b32_e32 v18, v187, v18, vcc
	v_lshlrev_b32_e32 v18, 2, v18
	ds_bpermute_b32 v18, v18, v0
	s_waitcnt lgkmcnt(0)
	v_add_f32_e32 v0, v0, v18
	v_fmamk_f32 v0, v0, 0x3c800000, v184
	v_cmp_gt_f32_e32 vcc, s74, v0
	v_mul_f32_e32 v18, 0x4b800000, v0
	s_nop 0
	v_cndmask_b32_e32 v0, v0, v18, vcc
	v_rsq_f32_e32 v0, v0
	s_nop 0
	v_mul_f32_e32 v18, 0x45800000, v0
	v_cndmask_b32_e32 v0, v0, v18, vcc
	v_mov_b32_e32 v22, v216
	v_mov_b32_e32 v23, v217
	v_mov_b32_e32 v24, v218
	v_mov_b32_e32 v25, v219
	v_mov_b32_e32 v18, v212
	v_mov_b32_e32 v19, v213
	v_mov_b32_e32 v20, v214
	v_mov_b32_e32 v21, v215
	v_mov_b32_e32 v26, v220
	v_mov_b32_e32 v27, v221
	v_mov_b32_e32 v28, v222
	v_mov_b32_e32 v29, v223
	v_mov_b32_e32 v30, v224
	v_mov_b32_e32 v31, v225
	v_mov_b32_e32 v32, v226
	v_mov_b32_e32 v33, v227
	v_mul_f32_e32 v0, v164, v0
	v_pk_mul_f32 v[24:25], v[46:47], v[24:25]
	v_pk_mul_f32 v[20:21], v[42:43], v[20:21]
	v_pk_mul_f32 v[18:19], v[44:45], v[18:19]
	v_pk_mul_f32 v[22:23], v[48:49], v[22:23]
	v_pk_mul_f32 v[32:33], v[38:39], v[32:33]
	v_pk_mul_f32 v[30:31], v[40:41], v[30:31]
	v_pk_mul_f32 v[28:29], v[34:35], v[28:29]
	v_pk_mul_f32 v[26:27], v[36:37], v[26:27]
	v_pk_mul_f32 v[20:21], v[20:21], v[0:1] op_sel_hi:[1,0]
	v_pk_mul_f32 v[18:19], v[18:19], v[0:1] op_sel_hi:[1,0]
	v_pk_mul_f32 v[24:25], v[24:25], v[0:1] op_sel_hi:[1,0]
	v_pk_mul_f32 v[22:23], v[22:23], v[0:1] op_sel_hi:[1,0]
	v_pk_mul_f32 v[32:33], v[32:33], v[0:1] op_sel_hi:[1,0]
	v_pk_mul_f32 v[30:31], v[30:31], v[0:1] op_sel_hi:[1,0]
	v_pk_mul_f32 v[28:29], v[28:29], v[0:1] op_sel_hi:[1,0]
	v_pk_mul_f32 v[26:27], v[26:27], v[0:1] op_sel_hi:[1,0]

;     __device__ __forceinline__ void operator()(const f32x4 (&acc)[2][2][4][2], const pg8::Unit& u, int wr, int wc, int fr, int fq, LAS unsigned char* sp) const {
;     ...
;                     if (act == 3) {
;                         float q = 0.f;
; #pragma unroll
;                         for (int bj = 0; bj < 2; ++bj)
; #pragma unroll
;                             for (int n = 0; n < 2; ++n) q += (v[bj][n][0] * v[bj][n][0] + v[bj][n][1] * v[bj][n][1]) + (v[bj][n][2] * v[bj][n][2] + v[bj][n][3] * v[bj][n][3]);
;                         q += __shfl_xor(q, 16); q += __shfl_xor(q, 32);
;                         const float ri = rsqrtf(q * (1.f / 64.f) + EPS) * osc;
; #pragma unroll
;                         for (int bj = 0; bj < 2; ++bj)
; #pragma unroll
;                             for (int n = 0; n < 2; ++n) { const f32x4 g = *(const f32x4*)(gn + 32 * bj + 8 * fq + 4 * n); v[bj][n] = v[bj][n] * g * ri; }
.LBB0_379:
	s_andn2_b64 vcc, exec, s[8:9]
	s_cbranch_vccnz .LBB0_381
	v_pk_mul_f32 v[2:3], v[26:27], v[26:27]
	v_pk_mul_f32 v[4:5], v[28:29], v[28:29]
	v_mul_f32_e32 v0, v24, v24
	v_pk_mov_b32 v[6:7], v[4:5], v[2:3] op_sel:[1,0]
	v_mov_b32_e32 v5, v3
	v_pk_add_f32 v[2:3], v[6:7], v[4:5]
	v_pk_mul_f32 v[4:5], v[30:31], v[30:31]
	v_pk_mul_f32 v[6:7], v[32:33], v[32:33]
	v_pk_add_f32 v[2:3], v[2:3], v[2:3] op_sel_hi:[0,1]
	v_pk_mov_b32 v[8:9], v[6:7], v[4:5] op_sel:[1,0]
	v_mov_b32_e32 v7, v5
	v_pk_add_f32 v[4:5], v[8:9], v[6:7]
	v_pk_fma_f32 v[6:7], v[24:25], v[24:25], v[0:1] op_sel_hi:[1,1,0]
	v_mul_f32_e32 v0, v22, v22
	v_pk_add_f32 v[4:5], v[4:5], v[4:5] op_sel_hi:[0,1]
	v_pk_fma_f32 v[8:9], v[22:23], v[22:23], v[0:1] op_sel_hi:[1,1,0]
	v_mul_f32_e32 v6, v20, v20
	v_mul_f32_e32 v8, v21, v21
	v_mul_f32_e32 v2, v18, v18
	v_mul_f32_e32 v4, v19, v19
	v_pk_add_f32 v[6:7], v[6:7], v[8:9]
	v_pk_add_f32 v[2:3], v[2:3], v[4:5]
	s_nop 0
	v_pk_add_f32 v[2:3], v[6:7], v[2:3]
	s_nop 0
	v_add_f32_e32 v0, v2, v3
	v_and_b32_e32 v3, 64, v187
	v_xor_b32_e32 v2, 16, v187
	v_add_u32_e32 v3, 64, v3
	v_cmp_lt_i32_e32 vcc, v2, v3
	s_nop 1
	v_cndmask_b32_e32 v2, v187, v2, vcc
	v_lshlrev_b32_e32 v2, 2, v2
	ds_bpermute_b32 v2, v2, v0
	s_waitcnt lgkmcnt(0)
	v_add_f32_e32 v0, v0, v2
	v_xor_b32_e32 v2, 32, v187
	v_cmp_lt_i32_e32 vcc, v2, v3
	s_nop 1
	v_cndmask_b32_e32 v2, v187, v2, vcc
	v_lshlrev_b32_e32 v2, 2, v2
	ds_bpermute_b32 v2, v2, v0
	s_waitcnt lgkmcnt(0)
	v_add_f32_e32 v0, v0, v2
	v_fmamk_f32 v0, v0, 0x3c800000, v184
	v_cmp_gt_f32_e32 vcc, s74, v0
	v_mul_f32_e32 v2, 0x4b800000, v0
	s_nop 0
	v_cndmask_b32_e32 v0, v0, v2, vcc
	v_rsq_f32_e32 v0, v0
	s_nop 0
	v_mul_f32_e32 v2, 0x45800000, v0
	v_cndmask_b32_e32 v0, v0, v2, vcc
	v_mov_b32_e32 v6, v216
	v_mov_b32_e32 v7, v217
	v_mov_b32_e32 v8, v218
	v_mov_b32_e32 v9, v219
	v_mov_b32_e32 v2, v212
	v_mov_b32_e32 v3, v213
	v_mov_b32_e32 v4, v214
	v_mov_b32_e32 v5, v215
	v_mov_b32_e32 v10, v220
	v_mov_b32_e32 v11, v221
	v_mov_b32_e32 v12, v222
	v_mov_b32_e32 v13, v223
	v_mov_b32_e32 v14, v224
	v_mov_b32_e32 v15, v225
	v_mov_b32_e32 v16, v226
	v_mov_b32_e32 v17, v227
	v_mul_f32_e32 v0, v164, v0
	v_pk_mul_f32 v[8:9], v[30:31], v[8:9]
	v_pk_mul_f32 v[4:5], v[26:27], v[4:5]
	v_pk_mul_f32 v[2:3], v[28:29], v[2:3]
	v_pk_mul_f32 v[6:7], v[32:33], v[6:7]
	v_pk_mul_f32 v[16:17], v[22:23], v[16:17]
	v_pk_mul_f32 v[14:15], v[24:25], v[14:15]
	v_pk_mul_f32 v[12:13], v[18:19], v[12:13]
	v_pk_mul_f32 v[10:11], v[20:21], v[10:11]
	v_pk_mul_f32 v[4:5], v[4:5], v[0:1] op_sel_hi:[1,0]
	v_pk_mul_f32 v[2:3], v[2:3], v[0:1] op_sel_hi:[1,0]
	v_pk_mul_f32 v[8:9], v[8:9], v[0:1] op_sel_hi:[1,0]
	v_pk_mul_f32 v[6:7], v[6:7], v[0:1] op_sel_hi:[1,0]
	v_pk_mul_f32 v[16:17], v[16:17], v[0:1] op_sel_hi:[1,0]
	v_pk_mul_f32 v[14:15], v[14:15], v[0:1] op_sel_hi:[1,0]
	v_pk_mul_f32 v[12:13], v[12:13], v[0:1] op_sel_hi:[1,0]
	v_pk_mul_f32 v[10:11], v[10:11], v[0:1] op_sel_hi:[1,0]
